# in_proj epilogue: loop-invariant gate-bias loads hoisted out of the 16 per-row-block sites (15 fewer vmcnt(0) drains per sigmoid unit), on top of prepare fix
# baseline (speedup 1.0000x reference)
; __device__ __forceinline__ float gelu_tanh(float x) { const float u = x * (-2.302208198f - 0.1029432397f * x * x); return x * __builtin_amdgcn_rcpf(1.f + __builtin_amdgcn_exp2f(u)); }
; __device__ __forceinline__ float sigmoidf_(float x) { return __builtin_amdgcn_rcpf(1.f + __builtin_amdgcn_exp2f(-1.4426950408889634f * x)); }
;     __device__ __forceinline__ void operator()(const f32x4 (&acc)[2][2][4][2], const pg8::Unit& u, int wr, int wc, int fr, int fq, LAS unsigned char* lds, int par) const {
;     ...
;                     const int c = cl + bj * 8;
;                     f32x4 v0 = acc[ai][bj][m][0], v1 = acc[ai][bj][m][1];
;                     if (fold) fold_apply(v0, v1, mu, rstd, cvb, c);
;                     if (kind == 0) {
; #pragma unroll
;                         for (int j = 0; j < 4; ++j) { v0[j] = gelu_tanh(v0[j]); v1[j] = gelu_tanh(v1[j]); }
;                     } else if (kind == 1 || kind == 2) {
;                         const int pos = row & (SEQ - 1), i0 = (c & 63) >> 1;
;                         const f32x4 r0 = *(const f32x4*)(rope + ((size_t)pos * 32 + i0) * 2), r1 = *(const f32x4*)(rope + ((size_t)pos * 32 + i0 + 2) * 2);
;                         const float sc = (kind == 1) ? 0.125f : 1.0f;
;                         f32x4 o0, o1;
;                         o0[0] = (v0[0] * r0[0] - v0[1] * r0[1]) * sc; o0[1] = (v0[1] * r0[0] + v0[0] * r0[1]) * sc;
;                         o0[2] = (v0[2] * r0[2] - v0[3] * r0[3]) * sc; o0[3] = (v0[3] * r0[2] + v0[2] * r0[3]) * sc;
;                         o1[0] = (v1[0] * r1[0] - v1[1] * r1[1]) * sc; o1[1] = (v1[1] * r1[0] + v1[0] * r1[1]) * sc;
;                         o1[2] = (v1[2] * r1[2] - v1[3] * r1[3]) * sc; o1[3] = (v1[3] * r1[2] + v1[2] * r1[3]) * sc;
;                         v0 = o0; v1 = o1;
;                     } else if (kind == 4) {
;                         const f32x4 b0 = *(const f32x4*)(bgate + gcol + c), b1 = *(const f32x4*)(bgate + gcol + c + 4);
; #pragma unroll
;                         for (int j = 0; j < 4; ++j) { v0[j] = sigmoidf_(v0[j] + b0[j]); v1[j] = sigmoidf_(v1[j] + b1[j]); }
.LBB0_573:
	v_lshl_add_u32 v150, s30, 8, v139
	s_lshl_b32 s17, s36, 8
	s_xor_b64 s[48:49], s[46:47], -1
	v_lshlrev_b32_e32 v0, 5, v150
	s_add_i32 s30, s17, 0xfffff200
	v_and_b32_e32 v187, 0x1f9e0, v0
	s_nor_b64 s[52:53], s[54:55], s[50:51]
	s_ashr_i32 s31, s30, 31
	v_cndmask_b32_e64 v148, 1.0, v208, s[54:55]
	s_mov_b64 s[50:51], -1
	s_and_b64 vcc, exec, s[48:49]
	s_cbranch_vccz .LBB0_581
	s_and_b64 vcc, exec, s[52:53]
	s_cbranch_vccz .LBB0_578
	s_andn2_b64 vcc, exec, s[26:27]
	v_mov_b32_e32 v159, v129
	v_mov_b32_e32 v158, v128
	v_mov_b32_e32 v157, v127
	v_mov_b32_e32 v156, v126
	v_mov_b32_e32 v163, v125
	v_mov_b32_e32 v162, v124
	v_mov_b32_e32 v161, v123
	v_mov_b32_e32 v160, v122
	s_cbranch_vccnz .LBB0_577
	v_lshl_add_u64 v[160:161], s[30:31], 2, v[140:141]
	global_load_dwordx4 v[212:215], v[160:161], off
	global_load_dwordx4 v[216:219], v[160:161], off offset:16
	global_load_dwordx4 v[220:223], v[160:161], off offset:32
	global_load_dwordx4 v[224:227], v[160:161], off offset:48
	s_waitcnt vmcnt(0)
	v_mov_b32_e32 v156, v212
	v_mov_b32_e32 v157, v213
	v_mov_b32_e32 v158, v214
	v_mov_b32_e32 v159, v215
	v_mov_b32_e32 v160, v216
	v_mov_b32_e32 v161, v217
	v_mov_b32_e32 v162, v218
	v_mov_b32_e32 v163, v219
	v_add_f32_e32 v0, v126, v156
	v_add_f32_e32 v151, v122, v160
	v_add_f32_e32 v156, v127, v157
	v_add_f32_e32 v157, v123, v161
	v_add_f32_e32 v158, v128, v158
	v_add_f32_e32 v160, v124, v162
	v_add_f32_e32 v159, v129, v159
	v_add_f32_e32 v161, v125, v163
	v_mul_f32_e32 v0, 0xbfb8aa3b, v0
	v_mul_f32_e32 v151, 0xbfb8aa3b, v151
	v_mul_f32_e32 v156, 0xbfb8aa3b, v156
	v_mul_f32_e32 v157, 0xbfb8aa3b, v157
	v_mul_f32_e32 v158, 0xbfb8aa3b, v158
	v_mul_f32_e32 v160, 0xbfb8aa3b, v160
	v_mul_f32_e32 v159, 0xbfb8aa3b, v159
	v_mul_f32_e32 v161, 0xbfb8aa3b, v161
	v_exp_f32_e32 v0, v0
	v_exp_f32_e32 v151, v151
	v_exp_f32_e32 v156, v156
	v_exp_f32_e32 v157, v157
	v_exp_f32_e32 v158, v158
	v_exp_f32_e32 v160, v160
	v_exp_f32_e32 v159, v159
	v_exp_f32_e32 v161, v161
	v_add_f32_e32 v0, 1.0, v0
	v_add_f32_e32 v151, 1.0, v151
	v_add_f32_e32 v162, 1.0, v156
	v_add_f32_e32 v163, 1.0, v157
	v_add_f32_e32 v158, 1.0, v158
	v_add_f32_e32 v172, 1.0, v160
	v_add_f32_e32 v159, 1.0, v159
	v_add_f32_e32 v173, 1.0, v161
	v_rcp_f32_e32 v156, v0
	v_rcp_f32_e32 v160, v151
	v_rcp_f32_e32 v157, v162
	v_rcp_f32_e32 v161, v163
	v_rcp_f32_e32 v158, v158
	v_rcp_f32_e32 v162, v172
	v_rcp_f32_e32 v159, v159
	v_rcp_f32_e32 v163, v173

; __device__ __forceinline__ float gelu_tanh(float x) { const float u = x * (-2.302208198f - 0.1029432397f * x * x); return x * __builtin_amdgcn_rcpf(1.f + __builtin_amdgcn_exp2f(u)); }
; __device__ __forceinline__ float sigmoidf_(float x) { return __builtin_amdgcn_rcpf(1.f + __builtin_amdgcn_exp2f(-1.4426950408889634f * x)); }
;     __device__ __forceinline__ void operator()(const f32x4 (&acc)[2][2][4][2], const pg8::Unit& u, int wr, int wc, int fr, int fq, LAS unsigned char* lds, int par) const {
;     ...
;                     const int c = cl + bj * 8;
;                     f32x4 v0 = acc[ai][bj][m][0], v1 = acc[ai][bj][m][1];
;                     if (fold) fold_apply(v0, v1, mu, rstd, cvb, c);
;                     if (kind == 0) {
; #pragma unroll
;                         for (int j = 0; j < 4; ++j) { v0[j] = gelu_tanh(v0[j]); v1[j] = gelu_tanh(v1[j]); }
;                     } else if (kind == 1 || kind == 2) {
;                         const int pos = row & (SEQ - 1), i0 = (c & 63) >> 1;
;                         const f32x4 r0 = *(const f32x4*)(rope + ((size_t)pos * 32 + i0) * 2), r1 = *(const f32x4*)(rope + ((size_t)pos * 32 + i0 + 2) * 2);
;                         const float sc = (kind == 1) ? 0.125f : 1.0f;
;                         f32x4 o0, o1;
;                         o0[0] = (v0[0] * r0[0] - v0[1] * r0[1]) * sc; o0[1] = (v0[1] * r0[0] + v0[0] * r0[1]) * sc;
;                         o0[2] = (v0[2] * r0[2] - v0[3] * r0[3]) * sc; o0[3] = (v0[3] * r0[2] + v0[2] * r0[3]) * sc;
;                         o1[0] = (v1[0] * r1[0] - v1[1] * r1[1]) * sc; o1[1] = (v1[1] * r1[0] + v1[0] * r1[1]) * sc;
;                         o1[2] = (v1[2] * r1[2] - v1[3] * r1[3]) * sc; o1[3] = (v1[3] * r1[2] + v1[2] * r1[3]) * sc;
;                         v0 = o0; v1 = o1;
;                     } else if (kind == 4) {
;                         const f32x4 b0 = *(const f32x4*)(bgate + gcol + c), b1 = *(const f32x4*)(bgate + gcol + c + 4);
; #pragma unroll
;                         for (int j = 0; j < 4; ++j) { v0[j] = sigmoidf_(v0[j] + b0[j]); v1[j] = sigmoidf_(v1[j] + b1[j]); }
.LBB0_587:
	v_cndmask_b32_e64 v122, 0, 1, s[48:49]
	v_cmp_ne_u32_e64 s[50:51], 1, v122
	v_cndmask_b32_e64 v122, 0, 1, s[52:53]
	s_mov_b64 s[38:39], -1
	s_andn2_b64 vcc, exec, s[48:49]
	v_cmp_ne_u32_e64 s[48:49], 1, v122
	s_cbranch_vccnz .LBB0_595
	s_and_b64 vcc, exec, s[48:49]
	s_cbranch_vccnz .LBB0_592
	s_andn2_b64 vcc, exec, s[26:27]
	v_mov_b32_e32 v125, v121
	v_mov_b32_e32 v124, v120
	v_mov_b32_e32 v123, v119
	v_mov_b32_e32 v122, v118
	v_mov_b32_e32 v155, v117
	v_mov_b32_e32 v154, v116
	v_mov_b32_e32 v153, v115
	v_mov_b32_e32 v152, v114
	s_cbranch_vccnz .LBB0_591
	v_mov_b32_e32 v122, v220
	v_mov_b32_e32 v123, v221
	v_mov_b32_e32 v124, v222
	v_mov_b32_e32 v125, v223
	v_mov_b32_e32 v152, v224
	v_mov_b32_e32 v153, v225
	v_mov_b32_e32 v154, v226
	v_mov_b32_e32 v155, v227
	v_add_f32_e32 v122, v118, v122
	v_add_f32_e32 v152, v114, v152
	v_add_f32_e32 v123, v119, v123
	v_add_f32_e32 v153, v115, v153
	v_add_f32_e32 v124, v120, v124
	v_add_f32_e32 v154, v116, v154
	v_add_f32_e32 v125, v121, v125
	v_add_f32_e32 v155, v117, v155
	v_mul_f32_e32 v122, 0xbfb8aa3b, v122
	v_mul_f32_e32 v152, 0xbfb8aa3b, v152
	v_mul_f32_e32 v123, 0xbfb8aa3b, v123
	v_mul_f32_e32 v153, 0xbfb8aa3b, v153
	v_mul_f32_e32 v124, 0xbfb8aa3b, v124
	v_mul_f32_e32 v154, 0xbfb8aa3b, v154
	v_mul_f32_e32 v125, 0xbfb8aa3b, v125
	v_mul_f32_e32 v155, 0xbfb8aa3b, v155
	v_exp_f32_e32 v122, v122
	v_exp_f32_e32 v152, v152
	v_exp_f32_e32 v123, v123
	v_exp_f32_e32 v153, v153
	v_exp_f32_e32 v124, v124
	v_exp_f32_e32 v154, v154
	v_exp_f32_e32 v125, v125
	v_exp_f32_e32 v155, v155
	v_add_f32_e32 v122, 1.0, v122
	v_add_f32_e32 v152, 1.0, v152
	v_add_f32_e32 v123, 1.0, v123
	v_add_f32_e32 v153, 1.0, v153
	v_add_f32_e32 v124, 1.0, v124
	v_add_f32_e32 v154, 1.0, v154
	v_add_f32_e32 v125, 1.0, v125
	v_add_f32_e32 v155, 1.0, v155
	v_rcp_f32_e32 v122, v122
	v_rcp_f32_e32 v152, v152
	v_rcp_f32_e32 v123, v123
	v_rcp_f32_e32 v153, v153
	v_rcp_f32_e32 v124, v124
	v_rcp_f32_e32 v154, v154
	v_rcp_f32_e32 v125, v125
	v_rcp_f32_e32 v155, v155

; __device__ __forceinline__ float gelu_tanh(float x) { const float u = x * (-2.302208198f - 0.1029432397f * x * x); return x * __builtin_amdgcn_rcpf(1.f + __builtin_amdgcn_exp2f(u)); }
;     __device__ __forceinline__ void operator()(const f32x4 (&acc)[2][2][4][2], const pg8::Unit& u, int wr, int wc, int fr, int fq, LAS unsigned char* lds, int par) const {
;     ...
;                 const int row = row0 + ai * 128 + m * 16, lrow = ai * 128 + wr * 64 + m * 16 + fr;
;                 float mu = 0.f, rstd = 1.f; if (fold) { mu = rsb[2 * lrow]; rstd = rsb[2 * lrow + 1]; }
;                 float s1 = 0.f, s2 = 0.f;
; #pragma unroll
;                 for (int bj = 0; bj < 2; ++bj) {
;                     const int c = cl + bj * 8;
;                     f32x4 v0 = acc[ai][bj][m][0], v1 = acc[ai][bj][m][1];
;                     if (fold) fold_apply(v0, v1, mu, rstd, cvb, c);
;                     if (kind == 0) {
; #pragma unroll
;                         for (int j = 0; j < 4; ++j) { v0[j] = gelu_tanh(v0[j]); v1[j] = gelu_tanh(v1[j]); }
;                     } else if (kind == 1 || kind == 2) {
;                         const int pos = row & (SEQ - 1), i0 = (c & 63) >> 1;
;                         const f32x4 r0 = *(const f32x4*)(rope + ((size_t)pos * 32 + i0) * 2), r1 = *(const f32x4*)(rope + ((size_t)pos * 32 + i0 + 2) * 2);
;                         const float sc = (kind == 1) ? 0.125f : 1.0f;
;                         f32x4 o0, o1;
;                         o0[0] = (v0[0] * r0[0] - v0[1] * r0[1]) * sc; o0[1] = (v0[1] * r0[0] + v0[0] * r0[1]) * sc;
;                         o0[2] = (v0[2] * r0[2] - v0[3] * r0[3]) * sc; o0[3] = (v0[3] * r0[2] + v0[2] * r0[3]) * sc;
;                         o1[0] = (v1[0] * r1[0] - v1[1] * r1[1]) * sc; o1[1] = (v1[1] * r1[0] + v1[0] * r1[1]) * sc;
;                         o1[2] = (v1[2] * r1[2] - v1[3] * r1[3]) * sc; o1[3] = (v1[3] * r1[2] + v1[2] * r1[3]) * sc;
;                         v0 = o0; v1 = o1;
;                     } else if (kind == 4) {
;                         const f32x4 b0 = *(const f32x4*)(bgate + gcol + c), b1 = *(const f32x4*)(bgate + gcol + c + 4);
; #pragma unroll
;                         for (int j = 0; j < 4; ++j) { v0[j] = sigmoidf_(v0[j] + b0[j]); v1[j] = sigmoidf_(v1[j] + b1[j]); }
.LBB0_605:
	v_or_b32_e32 v114, 16, v150
	v_lshlrev_b32_e32 v115, 5, v114
	v_and_b32_e32 v128, 0x1fbe0, v115
	s_and_b64 vcc, exec, s[50:51]
	s_mov_b64 s[36:37], -1
	s_cbranch_vccnz .LBB0_613
	s_and_b64 vcc, exec, s[48:49]
	s_cbranch_vccnz .LBB0_610
	s_andn2_b64 vcc, exec, s[26:27]
	v_mov_b32_e32 v123, v113
	v_mov_b32_e32 v122, v112
	v_mov_b32_e32 v121, v111
	v_mov_b32_e32 v120, v110
	v_mov_b32_e32 v127, v109
	v_mov_b32_e32 v126, v108
	v_mov_b32_e32 v125, v107
	v_mov_b32_e32 v124, v106
	s_cbranch_vccnz .LBB0_609
	v_mov_b32_e32 v120, v212
	v_mov_b32_e32 v121, v213
	v_mov_b32_e32 v122, v214
	v_mov_b32_e32 v123, v215
	v_mov_b32_e32 v124, v216
	v_mov_b32_e32 v125, v217
	v_mov_b32_e32 v126, v218
	v_mov_b32_e32 v127, v219
	v_add_f32_e32 v115, v110, v120
	v_add_f32_e32 v120, v106, v124
	v_add_f32_e32 v121, v111, v121
	v_add_f32_e32 v124, v107, v125
	v_add_f32_e32 v122, v112, v122
	v_add_f32_e32 v125, v108, v126
	v_add_f32_e32 v123, v113, v123
	v_add_f32_e32 v126, v109, v127
	v_mul_f32_e32 v115, 0xbfb8aa3b, v115
	v_mul_f32_e32 v120, 0xbfb8aa3b, v120
	v_mul_f32_e32 v121, 0xbfb8aa3b, v121
	v_mul_f32_e32 v124, 0xbfb8aa3b, v124
	v_mul_f32_e32 v122, 0xbfb8aa3b, v122
	v_mul_f32_e32 v125, 0xbfb8aa3b, v125
	v_mul_f32_e32 v123, 0xbfb8aa3b, v123
	v_mul_f32_e32 v126, 0xbfb8aa3b, v126
	v_exp_f32_e32 v115, v115
	v_exp_f32_e32 v120, v120
	v_exp_f32_e32 v121, v121
	v_exp_f32_e32 v124, v124
	v_exp_f32_e32 v122, v122
	v_exp_f32_e32 v125, v125
	v_exp_f32_e32 v123, v123
	v_exp_f32_e32 v126, v126
	v_add_f32_e32 v115, 1.0, v115
	v_add_f32_e32 v127, 1.0, v120
	v_add_f32_e32 v121, 1.0, v121
	v_add_f32_e32 v129, 1.0, v124
	v_add_f32_e32 v122, 1.0, v122
	v_add_f32_e32 v151, 1.0, v125
	v_add_f32_e32 v123, 1.0, v123
	v_add_f32_e32 v152, 1.0, v126
	v_rcp_f32_e32 v120, v115
	v_rcp_f32_e32 v124, v127
	v_rcp_f32_e32 v121, v121
	v_rcp_f32_e32 v125, v129
	v_rcp_f32_e32 v122, v122
	v_rcp_f32_e32 v126, v151
	v_rcp_f32_e32 v123, v123
	v_rcp_f32_e32 v127, v152

; __device__ __forceinline__ float gelu_tanh(float x) { const float u = x * (-2.302208198f - 0.1029432397f * x * x); return x * __builtin_amdgcn_rcpf(1.f + __builtin_amdgcn_exp2f(u)); }
; __device__ __forceinline__ float sigmoidf_(float x) { return __builtin_amdgcn_rcpf(1.f + __builtin_amdgcn_exp2f(-1.4426950408889634f * x)); }
;     __device__ __forceinline__ void operator()(const f32x4 (&acc)[2][2][4][2], const pg8::Unit& u, int wr, int wc, int fr, int fq, LAS unsigned char* lds, int par) const {
;     ...
;                     const int c = cl + bj * 8;
;                     f32x4 v0 = acc[ai][bj][m][0], v1 = acc[ai][bj][m][1];
;                     if (fold) fold_apply(v0, v1, mu, rstd, cvb, c);
;                     if (kind == 0) {
; #pragma unroll
;                         for (int j = 0; j < 4; ++j) { v0[j] = gelu_tanh(v0[j]); v1[j] = gelu_tanh(v1[j]); }
;                     } else if (kind == 1 || kind == 2) {
;                         const int pos = row & (SEQ - 1), i0 = (c & 63) >> 1;
;                         const f32x4 r0 = *(const f32x4*)(rope + ((size_t)pos * 32 + i0) * 2), r1 = *(const f32x4*)(rope + ((size_t)pos * 32 + i0 + 2) * 2);
;                         const float sc = (kind == 1) ? 0.125f : 1.0f;
;                         f32x4 o0, o1;
;                         o0[0] = (v0[0] * r0[0] - v0[1] * r0[1]) * sc; o0[1] = (v0[1] * r0[0] + v0[0] * r0[1]) * sc;
;                         o0[2] = (v0[2] * r0[2] - v0[3] * r0[3]) * sc; o0[3] = (v0[3] * r0[2] + v0[2] * r0[3]) * sc;
;                         o1[0] = (v1[0] * r1[0] - v1[1] * r1[1]) * sc; o1[1] = (v1[1] * r1[0] + v1[0] * r1[1]) * sc;
;                         o1[2] = (v1[2] * r1[2] - v1[3] * r1[3]) * sc; o1[3] = (v1[3] * r1[2] + v1[2] * r1[3]) * sc;
;                         v0 = o0; v1 = o1;
;                     } else if (kind == 4) {
;                         const f32x4 b0 = *(const f32x4*)(bgate + gcol + c), b1 = *(const f32x4*)(bgate + gcol + c + 4);
; #pragma unroll
;                         for (int j = 0; j < 4; ++j) { v0[j] = sigmoidf_(v0[j] + b0[j]); v1[j] = sigmoidf_(v1[j] + b1[j]); }
.LBB0_619:
	s_and_b64 vcc, exec, s[50:51]
	s_mov_b64 s[36:37], -1
	s_cbranch_vccnz .LBB0_627
	s_and_b64 vcc, exec, s[48:49]
	s_cbranch_vccnz .LBB0_624
	s_andn2_b64 vcc, exec, s[26:27]
	v_mov_b32_e32 v109, v105
	v_mov_b32_e32 v108, v104
	v_mov_b32_e32 v107, v103
	v_mov_b32_e32 v106, v102
	v_mov_b32_e32 v119, v101
	v_mov_b32_e32 v118, v100
	v_mov_b32_e32 v117, v99
	v_mov_b32_e32 v116, v98
	s_cbranch_vccnz .LBB0_623
	v_mov_b32_e32 v106, v220
	v_mov_b32_e32 v107, v221
	v_mov_b32_e32 v108, v222
	v_mov_b32_e32 v109, v223
	v_mov_b32_e32 v116, v224
	v_mov_b32_e32 v117, v225
	v_mov_b32_e32 v118, v226
	v_mov_b32_e32 v119, v227
	v_add_f32_e32 v106, v102, v106
	v_add_f32_e32 v116, v98, v116
	v_add_f32_e32 v107, v103, v107
	v_add_f32_e32 v117, v99, v117
	v_add_f32_e32 v108, v104, v108
	v_add_f32_e32 v118, v100, v118
	v_add_f32_e32 v109, v105, v109
	v_add_f32_e32 v119, v101, v119
	v_mul_f32_e32 v106, 0xbfb8aa3b, v106
	v_mul_f32_e32 v116, 0xbfb8aa3b, v116
	v_mul_f32_e32 v107, 0xbfb8aa3b, v107
	v_mul_f32_e32 v117, 0xbfb8aa3b, v117
	v_mul_f32_e32 v108, 0xbfb8aa3b, v108
	v_mul_f32_e32 v118, 0xbfb8aa3b, v118
	v_mul_f32_e32 v109, 0xbfb8aa3b, v109
	v_mul_f32_e32 v119, 0xbfb8aa3b, v119
	v_exp_f32_e32 v106, v106
	v_exp_f32_e32 v116, v116
	v_exp_f32_e32 v107, v107
	v_exp_f32_e32 v117, v117
	v_exp_f32_e32 v108, v108
	v_exp_f32_e32 v118, v118
	v_exp_f32_e32 v109, v109
	v_exp_f32_e32 v119, v119
	v_add_f32_e32 v106, 1.0, v106
	v_add_f32_e32 v116, 1.0, v116
	v_add_f32_e32 v107, 1.0, v107
	v_add_f32_e32 v117, 1.0, v117
	v_add_f32_e32 v108, 1.0, v108
	v_add_f32_e32 v118, 1.0, v118
	v_add_f32_e32 v109, 1.0, v109
	v_add_f32_e32 v119, 1.0, v119
	v_rcp_f32_e32 v106, v106
	v_rcp_f32_e32 v116, v116
	v_rcp_f32_e32 v107, v107
	v_rcp_f32_e32 v117, v117
	v_rcp_f32_e32 v108, v108
	v_rcp_f32_e32 v118, v118
	v_rcp_f32_e32 v109, v109
	v_rcp_f32_e32 v119, v119

; __device__ __forceinline__ float gelu_tanh(float x) { const float u = x * (-2.302208198f - 0.1029432397f * x * x); return x * __builtin_amdgcn_rcpf(1.f + __builtin_amdgcn_exp2f(u)); }
;     __device__ __forceinline__ void operator()(const f32x4 (&acc)[2][2][4][2], const pg8::Unit& u, int wr, int wc, int fr, int fq, LAS unsigned char* lds, int par) const {
;     ...
;                 const int row = row0 + ai * 128 + m * 16, lrow = ai * 128 + wr * 64 + m * 16 + fr;
;                 float mu = 0.f, rstd = 1.f; if (fold) { mu = rsb[2 * lrow]; rstd = rsb[2 * lrow + 1]; }
;                 float s1 = 0.f, s2 = 0.f;
; #pragma unroll
;                 for (int bj = 0; bj < 2; ++bj) {
;                     const int c = cl + bj * 8;
;                     f32x4 v0 = acc[ai][bj][m][0], v1 = acc[ai][bj][m][1];
;                     if (fold) fold_apply(v0, v1, mu, rstd, cvb, c);
;                     if (kind == 0) {
; #pragma unroll
;                         for (int j = 0; j < 4; ++j) { v0[j] = gelu_tanh(v0[j]); v1[j] = gelu_tanh(v1[j]); }
;                     } else if (kind == 1 || kind == 2) {
;                         const int pos = row & (SEQ - 1), i0 = (c & 63) >> 1;
;                         const f32x4 r0 = *(const f32x4*)(rope + ((size_t)pos * 32 + i0) * 2), r1 = *(const f32x4*)(rope + ((size_t)pos * 32 + i0 + 2) * 2);
;                         const float sc = (kind == 1) ? 0.125f : 1.0f;
;                         f32x4 o0, o1;
;                         o0[0] = (v0[0] * r0[0] - v0[1] * r0[1]) * sc; o0[1] = (v0[1] * r0[0] + v0[0] * r0[1]) * sc;
;                         o0[2] = (v0[2] * r0[2] - v0[3] * r0[3]) * sc; o0[3] = (v0[3] * r0[2] + v0[2] * r0[3]) * sc;
;                         o1[0] = (v1[0] * r1[0] - v1[1] * r1[1]) * sc; o1[1] = (v1[1] * r1[0] + v1[0] * r1[1]) * sc;
;                         o1[2] = (v1[2] * r1[2] - v1[3] * r1[3]) * sc; o1[3] = (v1[3] * r1[2] + v1[2] * r1[3]) * sc;
;                         v0 = o0; v1 = o1;
;                     } else if (kind == 4) {
;                         const f32x4 b0 = *(const f32x4*)(bgate + gcol + c), b1 = *(const f32x4*)(bgate + gcol + c + 4);
; #pragma unroll
;                         for (int j = 0; j < 4; ++j) { v0[j] = sigmoidf_(v0[j] + b0[j]); v1[j] = sigmoidf_(v1[j] + b1[j]); }
.LBB0_637:
	v_or_b32_e32 v98, 32, v150
	v_lshlrev_b32_e32 v99, 5, v98
	v_and_b32_e32 v112, 0x1fde0, v99
	s_and_b64 vcc, exec, s[50:51]
	s_mov_b64 s[36:37], -1
	s_cbranch_vccnz .LBB0_645
	s_and_b64 vcc, exec, s[48:49]
	s_cbranch_vccnz .LBB0_642
	s_andn2_b64 vcc, exec, s[26:27]
	v_mov_b32_e32 v107, v97
	v_mov_b32_e32 v106, v96
	v_mov_b32_e32 v105, v95
	v_mov_b32_e32 v104, v94
	v_mov_b32_e32 v111, v93
	v_mov_b32_e32 v110, v92
	v_mov_b32_e32 v109, v91
	v_mov_b32_e32 v108, v90
	s_cbranch_vccnz .LBB0_641
	v_mov_b32_e32 v104, v212
	v_mov_b32_e32 v105, v213
	v_mov_b32_e32 v106, v214
	v_mov_b32_e32 v107, v215
	v_mov_b32_e32 v108, v216
	v_mov_b32_e32 v109, v217
	v_mov_b32_e32 v110, v218
	v_mov_b32_e32 v111, v219
	v_add_f32_e32 v99, v94, v104
	v_add_f32_e32 v104, v90, v108
	v_add_f32_e32 v105, v95, v105
	v_add_f32_e32 v108, v91, v109
	v_add_f32_e32 v106, v96, v106
	v_add_f32_e32 v109, v92, v110
	v_add_f32_e32 v107, v97, v107
	v_add_f32_e32 v110, v93, v111
	v_mul_f32_e32 v99, 0xbfb8aa3b, v99
	v_mul_f32_e32 v104, 0xbfb8aa3b, v104
	v_mul_f32_e32 v105, 0xbfb8aa3b, v105
	v_mul_f32_e32 v108, 0xbfb8aa3b, v108
	v_mul_f32_e32 v106, 0xbfb8aa3b, v106
	v_mul_f32_e32 v109, 0xbfb8aa3b, v109
	v_mul_f32_e32 v107, 0xbfb8aa3b, v107
	v_mul_f32_e32 v110, 0xbfb8aa3b, v110
	v_exp_f32_e32 v99, v99
	v_exp_f32_e32 v104, v104
	v_exp_f32_e32 v105, v105
	v_exp_f32_e32 v108, v108
	v_exp_f32_e32 v106, v106
	v_exp_f32_e32 v109, v109
	v_exp_f32_e32 v107, v107
	v_exp_f32_e32 v110, v110
	v_add_f32_e32 v99, 1.0, v99
	v_add_f32_e32 v111, 1.0, v104
	v_add_f32_e32 v105, 1.0, v105
	v_add_f32_e32 v113, 1.0, v108
	v_add_f32_e32 v106, 1.0, v106
	v_add_f32_e32 v114, 1.0, v109
	v_add_f32_e32 v107, 1.0, v107
	v_add_f32_e32 v115, 1.0, v110
	v_rcp_f32_e32 v104, v99
	v_rcp_f32_e32 v108, v111
	v_rcp_f32_e32 v105, v105
	v_rcp_f32_e32 v109, v113
	v_rcp_f32_e32 v106, v106
	v_rcp_f32_e32 v110, v114
	v_rcp_f32_e32 v107, v107
	v_rcp_f32_e32 v111, v115

; __device__ __forceinline__ float gelu_tanh(float x) { const float u = x * (-2.302208198f - 0.1029432397f * x * x); return x * __builtin_amdgcn_rcpf(1.f + __builtin_amdgcn_exp2f(u)); }
; __device__ __forceinline__ float sigmoidf_(float x) { return __builtin_amdgcn_rcpf(1.f + __builtin_amdgcn_exp2f(-1.4426950408889634f * x)); }
;     __device__ __forceinline__ void operator()(const f32x4 (&acc)[2][2][4][2], const pg8::Unit& u, int wr, int wc, int fr, int fq, LAS unsigned char* lds, int par) const {
;     ...
;                     if (kind == 0) {
; #pragma unroll
;                         for (int j = 0; j < 4; ++j) { v0[j] = gelu_tanh(v0[j]); v1[j] = gelu_tanh(v1[j]); }
;                     } else if (kind == 1 || kind == 2) {
;                         const int pos = row & (SEQ - 1), i0 = (c & 63) >> 1;
;                         const f32x4 r0 = *(const f32x4*)(rope + ((size_t)pos * 32 + i0) * 2), r1 = *(const f32x4*)(rope + ((size_t)pos * 32 + i0 + 2) * 2);
;                         const float sc = (kind == 1) ? 0.125f : 1.0f;
;                         f32x4 o0, o1;
;                         o0[0] = (v0[0] * r0[0] - v0[1] * r0[1]) * sc; o0[1] = (v0[1] * r0[0] + v0[0] * r0[1]) * sc;
;                         o0[2] = (v0[2] * r0[2] - v0[3] * r0[3]) * sc; o0[3] = (v0[3] * r0[2] + v0[2] * r0[3]) * sc;
;                         o1[0] = (v1[0] * r1[0] - v1[1] * r1[1]) * sc; o1[1] = (v1[1] * r1[0] + v1[0] * r1[1]) * sc;
;                         o1[2] = (v1[2] * r1[2] - v1[3] * r1[3]) * sc; o1[3] = (v1[3] * r1[2] + v1[2] * r1[3]) * sc;
;                         v0 = o0; v1 = o1;
;                     } else if (kind == 4) {
;                         const f32x4 b0 = *(const f32x4*)(bgate + gcol + c), b1 = *(const f32x4*)(bgate + gcol + c + 4);
; #pragma unroll
;                         for (int j = 0; j < 4; ++j) { v0[j] = sigmoidf_(v0[j] + b0[j]); v1[j] = sigmoidf_(v1[j] + b1[j]); }
;                     }
.LBB0_651:
	s_and_b64 vcc, exec, s[50:51]
	s_mov_b64 s[36:37], -1
	s_cbranch_vccnz .LBB0_659
	s_and_b64 vcc, exec, s[48:49]
	s_cbranch_vccnz .LBB0_656
	s_andn2_b64 vcc, exec, s[26:27]
	v_mov_b32_e32 v93, v89
	v_mov_b32_e32 v92, v88
	v_mov_b32_e32 v91, v87
	v_mov_b32_e32 v90, v86
	v_mov_b32_e32 v103, v85
	v_mov_b32_e32 v102, v84
	v_mov_b32_e32 v101, v83
	v_mov_b32_e32 v100, v82
	s_cbranch_vccnz .LBB0_655
	v_mov_b32_e32 v90, v220
	v_mov_b32_e32 v91, v221
	v_mov_b32_e32 v92, v222
	v_mov_b32_e32 v93, v223
	v_mov_b32_e32 v100, v224
	v_mov_b32_e32 v101, v225
	v_mov_b32_e32 v102, v226
	v_mov_b32_e32 v103, v227
	v_add_f32_e32 v90, v86, v90
	v_add_f32_e32 v100, v82, v100
	v_add_f32_e32 v91, v87, v91
	v_add_f32_e32 v101, v83, v101
	v_add_f32_e32 v92, v88, v92
	v_add_f32_e32 v102, v84, v102
	v_add_f32_e32 v93, v89, v93
	v_add_f32_e32 v103, v85, v103
	v_mul_f32_e32 v90, 0xbfb8aa3b, v90
	v_mul_f32_e32 v100, 0xbfb8aa3b, v100
	v_mul_f32_e32 v91, 0xbfb8aa3b, v91
	v_mul_f32_e32 v101, 0xbfb8aa3b, v101
	v_mul_f32_e32 v92, 0xbfb8aa3b, v92
	v_mul_f32_e32 v102, 0xbfb8aa3b, v102
	v_mul_f32_e32 v93, 0xbfb8aa3b, v93
	v_mul_f32_e32 v103, 0xbfb8aa3b, v103
	v_exp_f32_e32 v90, v90
	v_exp_f32_e32 v100, v100
	v_exp_f32_e32 v91, v91
	v_exp_f32_e32 v101, v101
	v_exp_f32_e32 v92, v92
	v_exp_f32_e32 v102, v102
	v_exp_f32_e32 v93, v93
	v_exp_f32_e32 v103, v103
	v_add_f32_e32 v90, 1.0, v90
	v_add_f32_e32 v100, 1.0, v100
	v_add_f32_e32 v91, 1.0, v91
	v_add_f32_e32 v101, 1.0, v101
	v_add_f32_e32 v92, 1.0, v92
	v_add_f32_e32 v102, 1.0, v102
	v_add_f32_e32 v93, 1.0, v93
	v_add_f32_e32 v103, 1.0, v103
	v_rcp_f32_e32 v90, v90
	v_rcp_f32_e32 v100, v100
	v_rcp_f32_e32 v91, v91
	v_rcp_f32_e32 v101, v101
	v_rcp_f32_e32 v92, v92
	v_rcp_f32_e32 v102, v102
	v_rcp_f32_e32 v93, v93
	v_rcp_f32_e32 v103, v103

; __device__ __forceinline__ float gelu_tanh(float x) { const float u = x * (-2.302208198f - 0.1029432397f * x * x); return x * __builtin_amdgcn_rcpf(1.f + __builtin_amdgcn_exp2f(u)); }
;     __device__ __forceinline__ void operator()(const f32x4 (&acc)[2][2][4][2], const pg8::Unit& u, int wr, int wc, int fr, int fq, LAS unsigned char* lds, int par) const {
;     ...
;                 const int row = row0 + ai * 128 + m * 16, lrow = ai * 128 + wr * 64 + m * 16 + fr;
;                 float mu = 0.f, rstd = 1.f; if (fold) { mu = rsb[2 * lrow]; rstd = rsb[2 * lrow + 1]; }
;                 float s1 = 0.f, s2 = 0.f;
; #pragma unroll
;                 for (int bj = 0; bj < 2; ++bj) {
;                     const int c = cl + bj * 8;
;                     f32x4 v0 = acc[ai][bj][m][0], v1 = acc[ai][bj][m][1];
;                     if (fold) fold_apply(v0, v1, mu, rstd, cvb, c);
;                     if (kind == 0) {
; #pragma unroll
;                         for (int j = 0; j < 4; ++j) { v0[j] = gelu_tanh(v0[j]); v1[j] = gelu_tanh(v1[j]); }
;                     } else if (kind == 1 || kind == 2) {
;                         const int pos = row & (SEQ - 1), i0 = (c & 63) >> 1;
;                         const f32x4 r0 = *(const f32x4*)(rope + ((size_t)pos * 32 + i0) * 2), r1 = *(const f32x4*)(rope + ((size_t)pos * 32 + i0 + 2) * 2);
;                         const float sc = (kind == 1) ? 0.125f : 1.0f;
;                         f32x4 o0, o1;
;                         o0[0] = (v0[0] * r0[0] - v0[1] * r0[1]) * sc; o0[1] = (v0[1] * r0[0] + v0[0] * r0[1]) * sc;
;                         o0[2] = (v0[2] * r0[2] - v0[3] * r0[3]) * sc; o0[3] = (v0[3] * r0[2] + v0[2] * r0[3]) * sc;
;                         o1[0] = (v1[0] * r1[0] - v1[1] * r1[1]) * sc; o1[1] = (v1[1] * r1[0] + v1[0] * r1[1]) * sc;
;                         o1[2] = (v1[2] * r1[2] - v1[3] * r1[3]) * sc; o1[3] = (v1[3] * r1[2] + v1[2] * r1[3]) * sc;
;                         v0 = o0; v1 = o1;
;                     } else if (kind == 4) {
;                         const f32x4 b0 = *(const f32x4*)(bgate + gcol + c), b1 = *(const f32x4*)(bgate + gcol + c + 4);
; #pragma unroll
;                         for (int j = 0; j < 4; ++j) { v0[j] = sigmoidf_(v0[j] + b0[j]); v1[j] = sigmoidf_(v1[j] + b1[j]); }
;                     }
.LBB0_669:
	v_or_b32_e32 v82, 48, v150
	v_lshlrev_b32_e32 v83, 5, v82
	v_and_b32_e32 v96, 0x1ffe0, v83
	s_and_b64 vcc, exec, s[50:51]
	s_mov_b64 s[36:37], -1
	s_cbranch_vccnz .LBB0_677
	s_and_b64 vcc, exec, s[48:49]
	s_cbranch_vccnz .LBB0_674
	s_andn2_b64 vcc, exec, s[26:27]
	v_mov_b32_e32 v91, v81
	v_mov_b32_e32 v90, v80
	v_mov_b32_e32 v89, v79
	v_mov_b32_e32 v88, v78
	v_mov_b32_e32 v95, v77
	v_mov_b32_e32 v94, v76
	v_mov_b32_e32 v93, v75
	v_mov_b32_e32 v92, v74
	s_cbranch_vccnz .LBB0_673
	v_mov_b32_e32 v88, v212
	v_mov_b32_e32 v89, v213
	v_mov_b32_e32 v90, v214
	v_mov_b32_e32 v91, v215
	v_mov_b32_e32 v92, v216
	v_mov_b32_e32 v93, v217
	v_mov_b32_e32 v94, v218
	v_mov_b32_e32 v95, v219
	v_add_f32_e32 v83, v78, v88
	v_add_f32_e32 v88, v74, v92
	v_add_f32_e32 v89, v79, v89
	v_add_f32_e32 v92, v75, v93
	v_add_f32_e32 v90, v80, v90
	v_add_f32_e32 v93, v76, v94
	v_add_f32_e32 v91, v81, v91
	v_add_f32_e32 v94, v77, v95
	v_mul_f32_e32 v83, 0xbfb8aa3b, v83
	v_mul_f32_e32 v88, 0xbfb8aa3b, v88
	v_mul_f32_e32 v89, 0xbfb8aa3b, v89
	v_mul_f32_e32 v92, 0xbfb8aa3b, v92
	v_mul_f32_e32 v90, 0xbfb8aa3b, v90
	v_mul_f32_e32 v93, 0xbfb8aa3b, v93
	v_mul_f32_e32 v91, 0xbfb8aa3b, v91
	v_mul_f32_e32 v94, 0xbfb8aa3b, v94
	v_exp_f32_e32 v83, v83
	v_exp_f32_e32 v88, v88
	v_exp_f32_e32 v89, v89
	v_exp_f32_e32 v92, v92
	v_exp_f32_e32 v90, v90
	v_exp_f32_e32 v93, v93
	v_exp_f32_e32 v91, v91
	v_exp_f32_e32 v94, v94
	v_add_f32_e32 v83, 1.0, v83
	v_add_f32_e32 v95, 1.0, v88
	v_add_f32_e32 v89, 1.0, v89
	v_add_f32_e32 v97, 1.0, v92
	v_add_f32_e32 v90, 1.0, v90
	v_add_f32_e32 v98, 1.0, v93
	v_add_f32_e32 v91, 1.0, v91
	v_add_f32_e32 v99, 1.0, v94
	v_rcp_f32_e32 v88, v83
	v_rcp_f32_e32 v92, v95
	v_rcp_f32_e32 v89, v89
	v_rcp_f32_e32 v93, v97
	v_rcp_f32_e32 v90, v90
	v_rcp_f32_e32 v94, v98
	v_rcp_f32_e32 v91, v91
	v_rcp_f32_e32 v95, v99

; __device__ __forceinline__ float gelu_tanh(float x) { const float u = x * (-2.302208198f - 0.1029432397f * x * x); return x * __builtin_amdgcn_rcpf(1.f + __builtin_amdgcn_exp2f(u)); }
; __device__ __forceinline__ float sigmoidf_(float x) { return __builtin_amdgcn_rcpf(1.f + __builtin_amdgcn_exp2f(-1.4426950408889634f * x)); }
;     __device__ __forceinline__ void operator()(const f32x4 (&acc)[2][2][4][2], const pg8::Unit& u, int wr, int wc, int fr, int fq, LAS unsigned char* lds, int par) const {
;     ...
;                     if (kind == 0) {
; #pragma unroll
;                         for (int j = 0; j < 4; ++j) { v0[j] = gelu_tanh(v0[j]); v1[j] = gelu_tanh(v1[j]); }
;                     } else if (kind == 1 || kind == 2) {
;                         const int pos = row & (SEQ - 1), i0 = (c & 63) >> 1;
;                         const f32x4 r0 = *(const f32x4*)(rope + ((size_t)pos * 32 + i0) * 2), r1 = *(const f32x4*)(rope + ((size_t)pos * 32 + i0 + 2) * 2);
;                         const float sc = (kind == 1) ? 0.125f : 1.0f;
;                         f32x4 o0, o1;
;                         o0[0] = (v0[0] * r0[0] - v0[1] * r0[1]) * sc; o0[1] = (v0[1] * r0[0] + v0[0] * r0[1]) * sc;
;                         o0[2] = (v0[2] * r0[2] - v0[3] * r0[3]) * sc; o0[3] = (v0[3] * r0[2] + v0[2] * r0[3]) * sc;
;                         o1[0] = (v1[0] * r1[0] - v1[1] * r1[1]) * sc; o1[1] = (v1[1] * r1[0] + v1[0] * r1[1]) * sc;
;                         o1[2] = (v1[2] * r1[2] - v1[3] * r1[3]) * sc; o1[3] = (v1[3] * r1[2] + v1[2] * r1[3]) * sc;
;                         v0 = o0; v1 = o1;
;                     } else if (kind == 4) {
;                         const f32x4 b0 = *(const f32x4*)(bgate + gcol + c), b1 = *(const f32x4*)(bgate + gcol + c + 4);
; #pragma unroll
;                         for (int j = 0; j < 4; ++j) { v0[j] = sigmoidf_(v0[j] + b0[j]); v1[j] = sigmoidf_(v1[j] + b1[j]); }
;                     }
.LBB0_683:
	s_and_b64 vcc, exec, s[50:51]
	s_mov_b64 s[36:37], -1
	s_cbranch_vccnz .LBB0_691
	s_and_b64 vcc, exec, s[48:49]
	s_cbranch_vccnz .LBB0_688
	s_andn2_b64 vcc, exec, s[26:27]
	v_mov_b32_e32 v77, v73
	v_mov_b32_e32 v76, v72
	v_mov_b32_e32 v75, v71
	v_mov_b32_e32 v74, v70
	v_mov_b32_e32 v87, v69
	v_mov_b32_e32 v86, v68
	v_mov_b32_e32 v85, v67
	v_mov_b32_e32 v84, v66
	s_cbranch_vccnz .LBB0_687
	v_mov_b32_e32 v74, v220
	v_mov_b32_e32 v75, v221
	v_mov_b32_e32 v76, v222
	v_mov_b32_e32 v77, v223
	v_mov_b32_e32 v84, v224
	v_mov_b32_e32 v85, v225
	v_mov_b32_e32 v86, v226
	v_mov_b32_e32 v87, v227
	v_add_f32_e32 v74, v70, v74
	v_add_f32_e32 v84, v66, v84
	v_add_f32_e32 v75, v71, v75
	v_add_f32_e32 v85, v67, v85
	v_add_f32_e32 v76, v72, v76
	v_add_f32_e32 v86, v68, v86
	v_add_f32_e32 v77, v73, v77
	v_add_f32_e32 v87, v69, v87
	v_mul_f32_e32 v74, 0xbfb8aa3b, v74
	v_mul_f32_e32 v84, 0xbfb8aa3b, v84
	v_mul_f32_e32 v75, 0xbfb8aa3b, v75
	v_mul_f32_e32 v85, 0xbfb8aa3b, v85
	v_mul_f32_e32 v76, 0xbfb8aa3b, v76
	v_mul_f32_e32 v86, 0xbfb8aa3b, v86
	v_mul_f32_e32 v77, 0xbfb8aa3b, v77
	v_mul_f32_e32 v87, 0xbfb8aa3b, v87
	v_exp_f32_e32 v74, v74
	v_exp_f32_e32 v84, v84
	v_exp_f32_e32 v75, v75
	v_exp_f32_e32 v85, v85
	v_exp_f32_e32 v76, v76
	v_exp_f32_e32 v86, v86
	v_exp_f32_e32 v77, v77
	v_exp_f32_e32 v87, v87
	v_add_f32_e32 v74, 1.0, v74
	v_add_f32_e32 v84, 1.0, v84
	v_add_f32_e32 v75, 1.0, v75
	v_add_f32_e32 v85, 1.0, v85
	v_add_f32_e32 v76, 1.0, v76
	v_add_f32_e32 v86, 1.0, v86
	v_add_f32_e32 v77, 1.0, v77
	v_add_f32_e32 v87, 1.0, v87
	v_rcp_f32_e32 v74, v74
	v_rcp_f32_e32 v84, v84
	v_rcp_f32_e32 v75, v75
	v_rcp_f32_e32 v85, v85
	v_rcp_f32_e32 v76, v76
	v_rcp_f32_e32 v86, v86
	v_rcp_f32_e32 v77, v77
	v_rcp_f32_e32 v87, v87

; __device__ __forceinline__ float gelu_tanh(float x) { const float u = x * (-2.302208198f - 0.1029432397f * x * x); return x * __builtin_amdgcn_rcpf(1.f + __builtin_amdgcn_exp2f(u)); }
;     __device__ __forceinline__ void operator()(const f32x4 (&acc)[2][2][4][2], const pg8::Unit& u, int wr, int wc, int fr, int fq, LAS unsigned char* lds, int par) const {
;     ...
;                 const int row = row0 + ai * 128 + m * 16, lrow = ai * 128 + wr * 64 + m * 16 + fr;
;                 float mu = 0.f, rstd = 1.f; if (fold) { mu = rsb[2 * lrow]; rstd = rsb[2 * lrow + 1]; }
;                 float s1 = 0.f, s2 = 0.f;
; #pragma unroll
;                 for (int bj = 0; bj < 2; ++bj) {
;                     const int c = cl + bj * 8;
;                     f32x4 v0 = acc[ai][bj][m][0], v1 = acc[ai][bj][m][1];
;                     if (fold) fold_apply(v0, v1, mu, rstd, cvb, c);
;                     if (kind == 0) {
; #pragma unroll
;                         for (int j = 0; j < 4; ++j) { v0[j] = gelu_tanh(v0[j]); v1[j] = gelu_tanh(v1[j]); }
;                     } else if (kind == 1 || kind == 2) {
;                         const int pos = row & (SEQ - 1), i0 = (c & 63) >> 1;
;                         const f32x4 r0 = *(const f32x4*)(rope + ((size_t)pos * 32 + i0) * 2), r1 = *(const f32x4*)(rope + ((size_t)pos * 32 + i0 + 2) * 2);
;                         const float sc = (kind == 1) ? 0.125f : 1.0f;
;                         f32x4 o0, o1;
;                         o0[0] = (v0[0] * r0[0] - v0[1] * r0[1]) * sc; o0[1] = (v0[1] * r0[0] + v0[0] * r0[1]) * sc;
;                         o0[2] = (v0[2] * r0[2] - v0[3] * r0[3]) * sc; o0[3] = (v0[3] * r0[2] + v0[2] * r0[3]) * sc;
;                         o1[0] = (v1[0] * r1[0] - v1[1] * r1[1]) * sc; o1[1] = (v1[1] * r1[0] + v1[0] * r1[1]) * sc;
;                         o1[2] = (v1[2] * r1[2] - v1[3] * r1[3]) * sc; o1[3] = (v1[3] * r1[2] + v1[2] * r1[3]) * sc;
;                         v0 = o0; v1 = o1;
;                     } else if (kind == 4) {
;                         const f32x4 b0 = *(const f32x4*)(bgate + gcol + c), b1 = *(const f32x4*)(bgate + gcol + c + 4);
; #pragma unroll
;                         for (int j = 0; j < 4; ++j) { v0[j] = sigmoidf_(v0[j] + b0[j]); v1[j] = sigmoidf_(v1[j] + b1[j]); }
;                     }
.LBB0_701:
	v_add_u32_e32 v66, 0x80, v150
	v_lshlrev_b32_e32 v67, 5, v66
	v_and_b32_e32 v80, 0x1f9e0, v67
	s_and_b64 vcc, exec, s[50:51]
	s_mov_b64 s[36:37], -1
	s_cbranch_vccnz .LBB0_709
	s_and_b64 vcc, exec, s[48:49]
	s_cbranch_vccnz .LBB0_706
	s_andn2_b64 vcc, exec, s[26:27]
	v_mov_b32_e32 v75, v65
	v_mov_b32_e32 v74, v64
	v_mov_b32_e32 v73, v63
	v_mov_b32_e32 v72, v62
	v_mov_b32_e32 v79, v61
	v_mov_b32_e32 v78, v60
	v_mov_b32_e32 v77, v59
	v_mov_b32_e32 v76, v58
	s_cbranch_vccnz .LBB0_705
	v_mov_b32_e32 v72, v212
	v_mov_b32_e32 v73, v213
	v_mov_b32_e32 v74, v214
	v_mov_b32_e32 v75, v215
	v_mov_b32_e32 v76, v216
	v_mov_b32_e32 v77, v217
	v_mov_b32_e32 v78, v218
	v_mov_b32_e32 v79, v219
	v_add_f32_e32 v67, v62, v72
	v_add_f32_e32 v72, v58, v76
	v_add_f32_e32 v73, v63, v73
	v_add_f32_e32 v76, v59, v77
	v_add_f32_e32 v74, v64, v74
	v_add_f32_e32 v77, v60, v78
	v_add_f32_e32 v75, v65, v75
	v_add_f32_e32 v78, v61, v79
	v_mul_f32_e32 v67, 0xbfb8aa3b, v67
	v_mul_f32_e32 v72, 0xbfb8aa3b, v72
	v_mul_f32_e32 v73, 0xbfb8aa3b, v73
	v_mul_f32_e32 v76, 0xbfb8aa3b, v76
	v_mul_f32_e32 v74, 0xbfb8aa3b, v74
	v_mul_f32_e32 v77, 0xbfb8aa3b, v77
	v_mul_f32_e32 v75, 0xbfb8aa3b, v75
	v_mul_f32_e32 v78, 0xbfb8aa3b, v78
	v_exp_f32_e32 v67, v67
	v_exp_f32_e32 v72, v72
	v_exp_f32_e32 v73, v73
	v_exp_f32_e32 v76, v76
	v_exp_f32_e32 v74, v74
	v_exp_f32_e32 v77, v77
	v_exp_f32_e32 v75, v75
	v_exp_f32_e32 v78, v78
	v_add_f32_e32 v67, 1.0, v67
	v_add_f32_e32 v79, 1.0, v72
	v_add_f32_e32 v73, 1.0, v73
	v_add_f32_e32 v81, 1.0, v76
	v_add_f32_e32 v74, 1.0, v74
	v_add_f32_e32 v82, 1.0, v77
	v_add_f32_e32 v75, 1.0, v75
	v_add_f32_e32 v83, 1.0, v78
	v_rcp_f32_e32 v72, v67
	v_rcp_f32_e32 v76, v79
	v_rcp_f32_e32 v73, v73
	v_rcp_f32_e32 v77, v81
	v_rcp_f32_e32 v74, v74
	v_rcp_f32_e32 v78, v82
	v_rcp_f32_e32 v75, v75
	v_rcp_f32_e32 v79, v83

; __device__ __forceinline__ float gelu_tanh(float x) { const float u = x * (-2.302208198f - 0.1029432397f * x * x); return x * __builtin_amdgcn_rcpf(1.f + __builtin_amdgcn_exp2f(u)); }
; __device__ __forceinline__ float sigmoidf_(float x) { return __builtin_amdgcn_rcpf(1.f + __builtin_amdgcn_exp2f(-1.4426950408889634f * x)); }
;     __device__ __forceinline__ void operator()(const f32x4 (&acc)[2][2][4][2], const pg8::Unit& u, int wr, int wc, int fr, int fq, LAS unsigned char* lds, int par) const {
;     ...
;                     if (kind == 0) {
; #pragma unroll
;                         for (int j = 0; j < 4; ++j) { v0[j] = gelu_tanh(v0[j]); v1[j] = gelu_tanh(v1[j]); }
;                     } else if (kind == 1 || kind == 2) {
;                         const int pos = row & (SEQ - 1), i0 = (c & 63) >> 1;
;                         const f32x4 r0 = *(const f32x4*)(rope + ((size_t)pos * 32 + i0) * 2), r1 = *(const f32x4*)(rope + ((size_t)pos * 32 + i0 + 2) * 2);
;                         const float sc = (kind == 1) ? 0.125f : 1.0f;
;                         f32x4 o0, o1;
;                         o0[0] = (v0[0] * r0[0] - v0[1] * r0[1]) * sc; o0[1] = (v0[1] * r0[0] + v0[0] * r0[1]) * sc;
;                         o0[2] = (v0[2] * r0[2] - v0[3] * r0[3]) * sc; o0[3] = (v0[3] * r0[2] + v0[2] * r0[3]) * sc;
;                         o1[0] = (v1[0] * r1[0] - v1[1] * r1[1]) * sc; o1[1] = (v1[1] * r1[0] + v1[0] * r1[1]) * sc;
;                         o1[2] = (v1[2] * r1[2] - v1[3] * r1[3]) * sc; o1[3] = (v1[3] * r1[2] + v1[2] * r1[3]) * sc;
;                         v0 = o0; v1 = o1;
;                     } else if (kind == 4) {
;                         const f32x4 b0 = *(const f32x4*)(bgate + gcol + c), b1 = *(const f32x4*)(bgate + gcol + c + 4);
; #pragma unroll
;                         for (int j = 0; j < 4; ++j) { v0[j] = sigmoidf_(v0[j] + b0[j]); v1[j] = sigmoidf_(v1[j] + b1[j]); }
;                     }
.LBB0_715:
	s_and_b64 vcc, exec, s[50:51]
	s_mov_b64 s[36:37], -1
	s_cbranch_vccnz .LBB0_723
	s_and_b64 vcc, exec, s[48:49]
	s_cbranch_vccnz .LBB0_720
	s_andn2_b64 vcc, exec, s[26:27]
	v_mov_b32_e32 v61, v57
	v_mov_b32_e32 v60, v56
	v_mov_b32_e32 v59, v55
	v_mov_b32_e32 v58, v54
	v_mov_b32_e32 v71, v53
	v_mov_b32_e32 v70, v52
	v_mov_b32_e32 v69, v51
	v_mov_b32_e32 v68, v50
	s_cbranch_vccnz .LBB0_719
	v_mov_b32_e32 v58, v220
	v_mov_b32_e32 v59, v221
	v_mov_b32_e32 v60, v222
	v_mov_b32_e32 v61, v223
	v_mov_b32_e32 v68, v224
	v_mov_b32_e32 v69, v225
	v_mov_b32_e32 v70, v226
	v_mov_b32_e32 v71, v227
	v_add_f32_e32 v58, v54, v58
	v_add_f32_e32 v68, v50, v68
	v_add_f32_e32 v59, v55, v59
	v_add_f32_e32 v69, v51, v69
	v_add_f32_e32 v60, v56, v60
	v_add_f32_e32 v70, v52, v70
	v_add_f32_e32 v61, v57, v61
	v_add_f32_e32 v71, v53, v71
	v_mul_f32_e32 v58, 0xbfb8aa3b, v58
	v_mul_f32_e32 v68, 0xbfb8aa3b, v68
	v_mul_f32_e32 v59, 0xbfb8aa3b, v59
	v_mul_f32_e32 v69, 0xbfb8aa3b, v69
	v_mul_f32_e32 v60, 0xbfb8aa3b, v60
	v_mul_f32_e32 v70, 0xbfb8aa3b, v70
	v_mul_f32_e32 v61, 0xbfb8aa3b, v61
	v_mul_f32_e32 v71, 0xbfb8aa3b, v71
	v_exp_f32_e32 v58, v58
	v_exp_f32_e32 v68, v68
	v_exp_f32_e32 v59, v59
	v_exp_f32_e32 v69, v69
	v_exp_f32_e32 v60, v60
	v_exp_f32_e32 v70, v70
	v_exp_f32_e32 v61, v61
	v_exp_f32_e32 v71, v71
	v_add_f32_e32 v58, 1.0, v58
	v_add_f32_e32 v68, 1.0, v68
	v_add_f32_e32 v59, 1.0, v59
	v_add_f32_e32 v69, 1.0, v69
	v_add_f32_e32 v60, 1.0, v60
	v_add_f32_e32 v70, 1.0, v70
	v_add_f32_e32 v61, 1.0, v61
	v_add_f32_e32 v71, 1.0, v71
	v_rcp_f32_e32 v58, v58
	v_rcp_f32_e32 v68, v68
	v_rcp_f32_e32 v59, v59
	v_rcp_f32_e32 v69, v69
	v_rcp_f32_e32 v60, v60
	v_rcp_f32_e32 v70, v70
	v_rcp_f32_e32 v61, v61
	v_rcp_f32_e32 v71, v71

; __device__ __forceinline__ float gelu_tanh(float x) { const float u = x * (-2.302208198f - 0.1029432397f * x * x); return x * __builtin_amdgcn_rcpf(1.f + __builtin_amdgcn_exp2f(u)); }
;     __device__ __forceinline__ void operator()(const f32x4 (&acc)[2][2][4][2], const pg8::Unit& u, int wr, int wc, int fr, int fq, LAS unsigned char* lds, int par) const {
;     ...
;                 const int row = row0 + ai * 128 + m * 16, lrow = ai * 128 + wr * 64 + m * 16 + fr;
;                 float mu = 0.f, rstd = 1.f; if (fold) { mu = rsb[2 * lrow]; rstd = rsb[2 * lrow + 1]; }
;                 float s1 = 0.f, s2 = 0.f;
; #pragma unroll
;                 for (int bj = 0; bj < 2; ++bj) {
;                     const int c = cl + bj * 8;
;                     f32x4 v0 = acc[ai][bj][m][0], v1 = acc[ai][bj][m][1];
;                     if (fold) fold_apply(v0, v1, mu, rstd, cvb, c);
;                     if (kind == 0) {
; #pragma unroll
;                         for (int j = 0; j < 4; ++j) { v0[j] = gelu_tanh(v0[j]); v1[j] = gelu_tanh(v1[j]); }
;                     } else if (kind == 1 || kind == 2) {
;                         const int pos = row & (SEQ - 1), i0 = (c & 63) >> 1;
;                         const f32x4 r0 = *(const f32x4*)(rope + ((size_t)pos * 32 + i0) * 2), r1 = *(const f32x4*)(rope + ((size_t)pos * 32 + i0 + 2) * 2);
;                         const float sc = (kind == 1) ? 0.125f : 1.0f;
;                         f32x4 o0, o1;
;                         o0[0] = (v0[0] * r0[0] - v0[1] * r0[1]) * sc; o0[1] = (v0[1] * r0[0] + v0[0] * r0[1]) * sc;
;                         o0[2] = (v0[2] * r0[2] - v0[3] * r0[3]) * sc; o0[3] = (v0[3] * r0[2] + v0[2] * r0[3]) * sc;
;                         o1[0] = (v1[0] * r1[0] - v1[1] * r1[1]) * sc; o1[1] = (v1[1] * r1[0] + v1[0] * r1[1]) * sc;
;                         o1[2] = (v1[2] * r1[2] - v1[3] * r1[3]) * sc; o1[3] = (v1[3] * r1[2] + v1[2] * r1[3]) * sc;
;                         v0 = o0; v1 = o1;
;                     } else if (kind == 4) {
;                         const f32x4 b0 = *(const f32x4*)(bgate + gcol + c), b1 = *(const f32x4*)(bgate + gcol + c + 4);
; #pragma unroll
;                         for (int j = 0; j < 4; ++j) { v0[j] = sigmoidf_(v0[j] + b0[j]); v1[j] = sigmoidf_(v1[j] + b1[j]); }
;                     }
.LBB0_733:
	v_add_u32_e32 v50, 0x90, v150
	v_lshlrev_b32_e32 v51, 5, v50
	v_and_b32_e32 v64, 0x1fbe0, v51
	s_and_b64 vcc, exec, s[50:51]
	s_mov_b64 s[36:37], -1
	s_cbranch_vccnz .LBB0_741
	s_and_b64 vcc, exec, s[48:49]
	s_cbranch_vccnz .LBB0_738
	s_andn2_b64 vcc, exec, s[26:27]
	v_mov_b32_e32 v59, v49
	v_mov_b32_e32 v58, v48
	v_mov_b32_e32 v57, v47
	v_mov_b32_e32 v56, v46
	v_mov_b32_e32 v63, v45
	v_mov_b32_e32 v62, v44
	v_mov_b32_e32 v61, v43
	v_mov_b32_e32 v60, v42
	s_cbranch_vccnz .LBB0_737
	v_mov_b32_e32 v56, v212
	v_mov_b32_e32 v57, v213
	v_mov_b32_e32 v58, v214
	v_mov_b32_e32 v59, v215
	v_mov_b32_e32 v60, v216
	v_mov_b32_e32 v61, v217
	v_mov_b32_e32 v62, v218
	v_mov_b32_e32 v63, v219
	v_add_f32_e32 v51, v46, v56
	v_add_f32_e32 v56, v42, v60
	v_add_f32_e32 v57, v47, v57
	v_add_f32_e32 v60, v43, v61
	v_add_f32_e32 v58, v48, v58
	v_add_f32_e32 v61, v44, v62
	v_add_f32_e32 v59, v49, v59
	v_add_f32_e32 v62, v45, v63
	v_mul_f32_e32 v51, 0xbfb8aa3b, v51
	v_mul_f32_e32 v56, 0xbfb8aa3b, v56
	v_mul_f32_e32 v57, 0xbfb8aa3b, v57
	v_mul_f32_e32 v60, 0xbfb8aa3b, v60
	v_mul_f32_e32 v58, 0xbfb8aa3b, v58
	v_mul_f32_e32 v61, 0xbfb8aa3b, v61
	v_mul_f32_e32 v59, 0xbfb8aa3b, v59
	v_mul_f32_e32 v62, 0xbfb8aa3b, v62
	v_exp_f32_e32 v51, v51
	v_exp_f32_e32 v56, v56
	v_exp_f32_e32 v57, v57
	v_exp_f32_e32 v60, v60
	v_exp_f32_e32 v58, v58
	v_exp_f32_e32 v61, v61
	v_exp_f32_e32 v59, v59
	v_exp_f32_e32 v62, v62
	v_add_f32_e32 v51, 1.0, v51
	v_add_f32_e32 v63, 1.0, v56
	v_add_f32_e32 v57, 1.0, v57
	v_add_f32_e32 v65, 1.0, v60
	v_add_f32_e32 v58, 1.0, v58
	v_add_f32_e32 v66, 1.0, v61
	v_add_f32_e32 v59, 1.0, v59
	v_add_f32_e32 v67, 1.0, v62
	v_rcp_f32_e32 v56, v51
	v_rcp_f32_e32 v60, v63
	v_rcp_f32_e32 v57, v57
	v_rcp_f32_e32 v61, v65
	v_rcp_f32_e32 v58, v58
	v_rcp_f32_e32 v62, v66
	v_rcp_f32_e32 v59, v59
	v_rcp_f32_e32 v63, v67

; __device__ __forceinline__ float gelu_tanh(float x) { const float u = x * (-2.302208198f - 0.1029432397f * x * x); return x * __builtin_amdgcn_rcpf(1.f + __builtin_amdgcn_exp2f(u)); }
; __device__ __forceinline__ float sigmoidf_(float x) { return __builtin_amdgcn_rcpf(1.f + __builtin_amdgcn_exp2f(-1.4426950408889634f * x)); }
;     __device__ __forceinline__ void operator()(const f32x4 (&acc)[2][2][4][2], const pg8::Unit& u, int wr, int wc, int fr, int fq, LAS unsigned char* lds, int par) const {
;     ...
;                     if (kind == 0) {
; #pragma unroll
;                         for (int j = 0; j < 4; ++j) { v0[j] = gelu_tanh(v0[j]); v1[j] = gelu_tanh(v1[j]); }
;                     } else if (kind == 1 || kind == 2) {
;                         const int pos = row & (SEQ - 1), i0 = (c & 63) >> 1;
;                         const f32x4 r0 = *(const f32x4*)(rope + ((size_t)pos * 32 + i0) * 2), r1 = *(const f32x4*)(rope + ((size_t)pos * 32 + i0 + 2) * 2);
;                         const float sc = (kind == 1) ? 0.125f : 1.0f;
;                         f32x4 o0, o1;
;                         o0[0] = (v0[0] * r0[0] - v0[1] * r0[1]) * sc; o0[1] = (v0[1] * r0[0] + v0[0] * r0[1]) * sc;
;                         o0[2] = (v0[2] * r0[2] - v0[3] * r0[3]) * sc; o0[3] = (v0[3] * r0[2] + v0[2] * r0[3]) * sc;
;                         o1[0] = (v1[0] * r1[0] - v1[1] * r1[1]) * sc; o1[1] = (v1[1] * r1[0] + v1[0] * r1[1]) * sc;
;                         o1[2] = (v1[2] * r1[2] - v1[3] * r1[3]) * sc; o1[3] = (v1[3] * r1[2] + v1[2] * r1[3]) * sc;
;                         v0 = o0; v1 = o1;
;                     } else if (kind == 4) {
;                         const f32x4 b0 = *(const f32x4*)(bgate + gcol + c), b1 = *(const f32x4*)(bgate + gcol + c + 4);
; #pragma unroll
;                         for (int j = 0; j < 4; ++j) { v0[j] = sigmoidf_(v0[j] + b0[j]); v1[j] = sigmoidf_(v1[j] + b1[j]); }
;                     }
.LBB0_747:
	s_and_b64 vcc, exec, s[50:51]
	s_mov_b64 s[36:37], -1
	s_cbranch_vccnz .LBB0_755
	s_and_b64 vcc, exec, s[48:49]
	s_cbranch_vccnz .LBB0_752
	s_andn2_b64 vcc, exec, s[26:27]
	v_mov_b32_e32 v45, v41
	v_mov_b32_e32 v44, v40
	v_mov_b32_e32 v43, v39
	v_mov_b32_e32 v42, v38
	v_mov_b32_e32 v55, v37
	v_mov_b32_e32 v54, v36
	v_mov_b32_e32 v53, v35
	v_mov_b32_e32 v52, v34
	s_cbranch_vccnz .LBB0_751
	v_mov_b32_e32 v42, v220
	v_mov_b32_e32 v43, v221
	v_mov_b32_e32 v44, v222
	v_mov_b32_e32 v45, v223
	v_mov_b32_e32 v52, v224
	v_mov_b32_e32 v53, v225
	v_mov_b32_e32 v54, v226
	v_mov_b32_e32 v55, v227
	v_add_f32_e32 v42, v38, v42
	v_add_f32_e32 v52, v34, v52
	v_add_f32_e32 v43, v39, v43
	v_add_f32_e32 v53, v35, v53
	v_add_f32_e32 v44, v40, v44
	v_add_f32_e32 v54, v36, v54
	v_add_f32_e32 v45, v41, v45
	v_add_f32_e32 v55, v37, v55
	v_mul_f32_e32 v42, 0xbfb8aa3b, v42
	v_mul_f32_e32 v52, 0xbfb8aa3b, v52
	v_mul_f32_e32 v43, 0xbfb8aa3b, v43
	v_mul_f32_e32 v53, 0xbfb8aa3b, v53
	v_mul_f32_e32 v44, 0xbfb8aa3b, v44
	v_mul_f32_e32 v54, 0xbfb8aa3b, v54
	v_mul_f32_e32 v45, 0xbfb8aa3b, v45
	v_mul_f32_e32 v55, 0xbfb8aa3b, v55
	v_exp_f32_e32 v42, v42
	v_exp_f32_e32 v52, v52
	v_exp_f32_e32 v43, v43
	v_exp_f32_e32 v53, v53
	v_exp_f32_e32 v44, v44
	v_exp_f32_e32 v54, v54
	v_exp_f32_e32 v45, v45
	v_exp_f32_e32 v55, v55
	v_add_f32_e32 v42, 1.0, v42
	v_add_f32_e32 v52, 1.0, v52
	v_add_f32_e32 v43, 1.0, v43
	v_add_f32_e32 v53, 1.0, v53
	v_add_f32_e32 v44, 1.0, v44
	v_add_f32_e32 v54, 1.0, v54
	v_add_f32_e32 v45, 1.0, v45
	v_add_f32_e32 v55, 1.0, v55
	v_rcp_f32_e32 v42, v42
	v_rcp_f32_e32 v52, v52
	v_rcp_f32_e32 v43, v43
	v_rcp_f32_e32 v53, v53
	v_rcp_f32_e32 v44, v44
	v_rcp_f32_e32 v54, v54
	v_rcp_f32_e32 v45, v45
	v_rcp_f32_e32 v55, v55

; __device__ __forceinline__ float gelu_tanh(float x) { const float u = x * (-2.302208198f - 0.1029432397f * x * x); return x * __builtin_amdgcn_rcpf(1.f + __builtin_amdgcn_exp2f(u)); }
;     __device__ __forceinline__ void operator()(const f32x4 (&acc)[2][2][4][2], const pg8::Unit& u, int wr, int wc, int fr, int fq, LAS unsigned char* lds, int par) const {
;     ...
;                 const int row = row0 + ai * 128 + m * 16, lrow = ai * 128 + wr * 64 + m * 16 + fr;
;                 float mu = 0.f, rstd = 1.f; if (fold) { mu = rsb[2 * lrow]; rstd = rsb[2 * lrow + 1]; }
;                 float s1 = 0.f, s2 = 0.f;
; #pragma unroll
;                 for (int bj = 0; bj < 2; ++bj) {
;                     const int c = cl + bj * 8;
;                     f32x4 v0 = acc[ai][bj][m][0], v1 = acc[ai][bj][m][1];
;                     if (fold) fold_apply(v0, v1, mu, rstd, cvb, c);
;                     if (kind == 0) {
; #pragma unroll
;                         for (int j = 0; j < 4; ++j) { v0[j] = gelu_tanh(v0[j]); v1[j] = gelu_tanh(v1[j]); }
;                     } else if (kind == 1 || kind == 2) {
;                         const int pos = row & (SEQ - 1), i0 = (c & 63) >> 1;
;                         const f32x4 r0 = *(const f32x4*)(rope + ((size_t)pos * 32 + i0) * 2), r1 = *(const f32x4*)(rope + ((size_t)pos * 32 + i0 + 2) * 2);
;                         const float sc = (kind == 1) ? 0.125f : 1.0f;
;                         f32x4 o0, o1;
;                         o0[0] = (v0[0] * r0[0] - v0[1] * r0[1]) * sc; o0[1] = (v0[1] * r0[0] + v0[0] * r0[1]) * sc;
;                         o0[2] = (v0[2] * r0[2] - v0[3] * r0[3]) * sc; o0[3] = (v0[3] * r0[2] + v0[2] * r0[3]) * sc;
;                         o1[0] = (v1[0] * r1[0] - v1[1] * r1[1]) * sc; o1[1] = (v1[1] * r1[0] + v1[0] * r1[1]) * sc;
;                         o1[2] = (v1[2] * r1[2] - v1[3] * r1[3]) * sc; o1[3] = (v1[3] * r1[2] + v1[2] * r1[3]) * sc;
;                         v0 = o0; v1 = o1;
;                     } else if (kind == 4) {
;                         const f32x4 b0 = *(const f32x4*)(bgate + gcol + c), b1 = *(const f32x4*)(bgate + gcol + c + 4);
; #pragma unroll
;                         for (int j = 0; j < 4; ++j) { v0[j] = sigmoidf_(v0[j] + b0[j]); v1[j] = sigmoidf_(v1[j] + b1[j]); }
;                     }
.LBB0_765:
	v_add_u32_e32 v34, 0xa0, v150
	v_lshlrev_b32_e32 v35, 5, v34
	v_and_b32_e32 v48, 0x1fde0, v35
	s_and_b64 vcc, exec, s[50:51]
	s_mov_b64 s[36:37], -1
	s_cbranch_vccnz .LBB0_773
	s_and_b64 vcc, exec, s[48:49]
	s_cbranch_vccnz .LBB0_770
	s_andn2_b64 vcc, exec, s[26:27]
	v_mov_b32_e32 v43, v33
	v_mov_b32_e32 v42, v32
	v_mov_b32_e32 v41, v31
	v_mov_b32_e32 v40, v30
	v_mov_b32_e32 v47, v29
	v_mov_b32_e32 v46, v28
	v_mov_b32_e32 v45, v27
	v_mov_b32_e32 v44, v26
	s_cbranch_vccnz .LBB0_769
	v_mov_b32_e32 v40, v212
	v_mov_b32_e32 v41, v213
	v_mov_b32_e32 v42, v214
	v_mov_b32_e32 v43, v215
	v_mov_b32_e32 v44, v216
	v_mov_b32_e32 v45, v217
	v_mov_b32_e32 v46, v218
	v_mov_b32_e32 v47, v219
	v_add_f32_e32 v35, v30, v40
	v_add_f32_e32 v40, v26, v44
	v_add_f32_e32 v41, v31, v41
	v_add_f32_e32 v44, v27, v45
	v_add_f32_e32 v42, v32, v42
	v_add_f32_e32 v45, v28, v46
	v_add_f32_e32 v43, v33, v43
	v_add_f32_e32 v46, v29, v47
	v_mul_f32_e32 v35, 0xbfb8aa3b, v35
	v_mul_f32_e32 v40, 0xbfb8aa3b, v40
	v_mul_f32_e32 v41, 0xbfb8aa3b, v41
	v_mul_f32_e32 v44, 0xbfb8aa3b, v44
	v_mul_f32_e32 v42, 0xbfb8aa3b, v42
	v_mul_f32_e32 v45, 0xbfb8aa3b, v45
	v_mul_f32_e32 v43, 0xbfb8aa3b, v43
	v_mul_f32_e32 v46, 0xbfb8aa3b, v46
	v_exp_f32_e32 v35, v35
	v_exp_f32_e32 v40, v40
	v_exp_f32_e32 v41, v41
	v_exp_f32_e32 v44, v44
	v_exp_f32_e32 v42, v42
	v_exp_f32_e32 v45, v45
	v_exp_f32_e32 v43, v43
	v_exp_f32_e32 v46, v46
	v_add_f32_e32 v35, 1.0, v35
	v_add_f32_e32 v47, 1.0, v40
	v_add_f32_e32 v41, 1.0, v41
	v_add_f32_e32 v49, 1.0, v44
	v_add_f32_e32 v42, 1.0, v42
	v_add_f32_e32 v50, 1.0, v45
	v_add_f32_e32 v43, 1.0, v43
	v_add_f32_e32 v51, 1.0, v46
	v_rcp_f32_e32 v40, v35
	v_rcp_f32_e32 v44, v47
	v_rcp_f32_e32 v41, v41
	v_rcp_f32_e32 v45, v49
	v_rcp_f32_e32 v42, v42
	v_rcp_f32_e32 v46, v50
	v_rcp_f32_e32 v43, v43
	v_rcp_f32_e32 v47, v51

; __device__ __forceinline__ float gelu_tanh(float x) { const float u = x * (-2.302208198f - 0.1029432397f * x * x); return x * __builtin_amdgcn_rcpf(1.f + __builtin_amdgcn_exp2f(u)); }
; __device__ __forceinline__ float sigmoidf_(float x) { return __builtin_amdgcn_rcpf(1.f + __builtin_amdgcn_exp2f(-1.4426950408889634f * x)); }
;     __device__ __forceinline__ void operator()(const f32x4 (&acc)[2][2][4][2], const pg8::Unit& u, int wr, int wc, int fr, int fq, LAS unsigned char* lds, int par) const {
;     ...
;                     if (kind == 0) {
; #pragma unroll
;                         for (int j = 0; j < 4; ++j) { v0[j] = gelu_tanh(v0[j]); v1[j] = gelu_tanh(v1[j]); }
;                     } else if (kind == 1 || kind == 2) {
;                         const int pos = row & (SEQ - 1), i0 = (c & 63) >> 1;
;                         const f32x4 r0 = *(const f32x4*)(rope + ((size_t)pos * 32 + i0) * 2), r1 = *(const f32x4*)(rope + ((size_t)pos * 32 + i0 + 2) * 2);
;                         const float sc = (kind == 1) ? 0.125f : 1.0f;
;                         f32x4 o0, o1;
;                         o0[0] = (v0[0] * r0[0] - v0[1] * r0[1]) * sc; o0[1] = (v0[1] * r0[0] + v0[0] * r0[1]) * sc;
;                         o0[2] = (v0[2] * r0[2] - v0[3] * r0[3]) * sc; o0[3] = (v0[3] * r0[2] + v0[2] * r0[3]) * sc;
;                         o1[0] = (v1[0] * r1[0] - v1[1] * r1[1]) * sc; o1[1] = (v1[1] * r1[0] + v1[0] * r1[1]) * sc;
;                         o1[2] = (v1[2] * r1[2] - v1[3] * r1[3]) * sc; o1[3] = (v1[3] * r1[2] + v1[2] * r1[3]) * sc;
;                         v0 = o0; v1 = o1;
;                     } else if (kind == 4) {
;                         const f32x4 b0 = *(const f32x4*)(bgate + gcol + c), b1 = *(const f32x4*)(bgate + gcol + c + 4);
; #pragma unroll
;                         for (int j = 0; j < 4; ++j) { v0[j] = sigmoidf_(v0[j] + b0[j]); v1[j] = sigmoidf_(v1[j] + b1[j]); }
;                     }
.LBB0_779:
	s_and_b64 vcc, exec, s[50:51]
	s_mov_b64 s[36:37], -1
	s_cbranch_vccnz .LBB0_787
	s_and_b64 vcc, exec, s[48:49]
	s_cbranch_vccnz .LBB0_784
	s_andn2_b64 vcc, exec, s[26:27]
	v_mov_b32_e32 v29, v25
	v_mov_b32_e32 v28, v24
	v_mov_b32_e32 v27, v23
	v_mov_b32_e32 v26, v22
	v_mov_b32_e32 v39, v21
	v_mov_b32_e32 v38, v20
	v_mov_b32_e32 v37, v19
	v_mov_b32_e32 v36, v18
	s_cbranch_vccnz .LBB0_783
	v_mov_b32_e32 v26, v220
	v_mov_b32_e32 v27, v221
	v_mov_b32_e32 v28, v222
	v_mov_b32_e32 v29, v223
	v_mov_b32_e32 v36, v224
	v_mov_b32_e32 v37, v225
	v_mov_b32_e32 v38, v226
	v_mov_b32_e32 v39, v227
	v_add_f32_e32 v26, v22, v26
	v_add_f32_e32 v36, v18, v36
	v_add_f32_e32 v27, v23, v27
	v_add_f32_e32 v37, v19, v37
	v_add_f32_e32 v28, v24, v28
	v_add_f32_e32 v38, v20, v38
	v_add_f32_e32 v29, v25, v29
	v_add_f32_e32 v39, v21, v39
	v_mul_f32_e32 v26, 0xbfb8aa3b, v26
	v_mul_f32_e32 v36, 0xbfb8aa3b, v36
	v_mul_f32_e32 v27, 0xbfb8aa3b, v27
	v_mul_f32_e32 v37, 0xbfb8aa3b, v37
	v_mul_f32_e32 v28, 0xbfb8aa3b, v28
	v_mul_f32_e32 v38, 0xbfb8aa3b, v38
	v_mul_f32_e32 v29, 0xbfb8aa3b, v29
	v_mul_f32_e32 v39, 0xbfb8aa3b, v39
	v_exp_f32_e32 v26, v26
	v_exp_f32_e32 v36, v36
	v_exp_f32_e32 v27, v27
	v_exp_f32_e32 v37, v37
	v_exp_f32_e32 v28, v28
	v_exp_f32_e32 v38, v38
	v_exp_f32_e32 v29, v29
	v_exp_f32_e32 v39, v39
	v_add_f32_e32 v26, 1.0, v26
	v_add_f32_e32 v36, 1.0, v36
	v_add_f32_e32 v27, 1.0, v27
	v_add_f32_e32 v37, 1.0, v37
	v_add_f32_e32 v28, 1.0, v28
	v_add_f32_e32 v38, 1.0, v38
	v_add_f32_e32 v29, 1.0, v29
	v_add_f32_e32 v39, 1.0, v39
	v_rcp_f32_e32 v26, v26
	v_rcp_f32_e32 v36, v36
	v_rcp_f32_e32 v27, v27
	v_rcp_f32_e32 v37, v37
	v_rcp_f32_e32 v28, v28
	v_rcp_f32_e32 v38, v38
	v_rcp_f32_e32 v29, v29
	v_rcp_f32_e32 v39, v39

; __device__ __forceinline__ float gelu_tanh(float x) { const float u = x * (-2.302208198f - 0.1029432397f * x * x); return x * __builtin_amdgcn_rcpf(1.f + __builtin_amdgcn_exp2f(u)); }
;     __device__ __forceinline__ void operator()(const f32x4 (&acc)[2][2][4][2], const pg8::Unit& u, int wr, int wc, int fr, int fq, LAS unsigned char* lds, int par) const {
;     ...
;                 const int row = row0 + ai * 128 + m * 16, lrow = ai * 128 + wr * 64 + m * 16 + fr;
;                 float mu = 0.f, rstd = 1.f; if (fold) { mu = rsb[2 * lrow]; rstd = rsb[2 * lrow + 1]; }
;                 float s1 = 0.f, s2 = 0.f;
; #pragma unroll
;                 for (int bj = 0; bj < 2; ++bj) {
;                     const int c = cl + bj * 8;
;                     f32x4 v0 = acc[ai][bj][m][0], v1 = acc[ai][bj][m][1];
;                     if (fold) fold_apply(v0, v1, mu, rstd, cvb, c);
;                     if (kind == 0) {
; #pragma unroll
;                         for (int j = 0; j < 4; ++j) { v0[j] = gelu_tanh(v0[j]); v1[j] = gelu_tanh(v1[j]); }
;                     } else if (kind == 1 || kind == 2) {
;                         const int pos = row & (SEQ - 1), i0 = (c & 63) >> 1;
;                         const f32x4 r0 = *(const f32x4*)(rope + ((size_t)pos * 32 + i0) * 2), r1 = *(const f32x4*)(rope + ((size_t)pos * 32 + i0 + 2) * 2);
;                         const float sc = (kind == 1) ? 0.125f : 1.0f;
;                         f32x4 o0, o1;
;                         o0[0] = (v0[0] * r0[0] - v0[1] * r0[1]) * sc; o0[1] = (v0[1] * r0[0] + v0[0] * r0[1]) * sc;
;                         o0[2] = (v0[2] * r0[2] - v0[3] * r0[3]) * sc; o0[3] = (v0[3] * r0[2] + v0[2] * r0[3]) * sc;
;                         o1[0] = (v1[0] * r1[0] - v1[1] * r1[1]) * sc; o1[1] = (v1[1] * r1[0] + v1[0] * r1[1]) * sc;
;                         o1[2] = (v1[2] * r1[2] - v1[3] * r1[3]) * sc; o1[3] = (v1[3] * r1[2] + v1[2] * r1[3]) * sc;
;                         v0 = o0; v1 = o1;
;                     } else if (kind == 4) {
;                         const f32x4 b0 = *(const f32x4*)(bgate + gcol + c), b1 = *(const f32x4*)(bgate + gcol + c + 4);
; #pragma unroll
;                         for (int j = 0; j < 4; ++j) { v0[j] = sigmoidf_(v0[j] + b0[j]); v1[j] = sigmoidf_(v1[j] + b1[j]); }
;                     }
.LBB0_797:
	v_add_u32_e32 v18, 0xb0, v150
	v_lshlrev_b32_e32 v19, 5, v18
	v_and_b32_e32 v32, 0x1ffe0, v19
	s_and_b64 vcc, exec, s[50:51]
	s_mov_b64 s[36:37], -1
	s_cbranch_vccnz .LBB0_805
	s_and_b64 vcc, exec, s[48:49]
	s_cbranch_vccnz .LBB0_802
	s_andn2_b64 vcc, exec, s[26:27]
	v_mov_b32_e32 v27, v17
	v_mov_b32_e32 v26, v16
	v_mov_b32_e32 v25, v15
	v_mov_b32_e32 v24, v14
	v_mov_b32_e32 v31, v13
	v_mov_b32_e32 v30, v12
	v_mov_b32_e32 v29, v11
	v_mov_b32_e32 v28, v10
	s_cbranch_vccnz .LBB0_801
	v_mov_b32_e32 v24, v212
	v_mov_b32_e32 v25, v213
	v_mov_b32_e32 v26, v214
	v_mov_b32_e32 v27, v215
	v_mov_b32_e32 v28, v216
	v_mov_b32_e32 v29, v217
	v_mov_b32_e32 v30, v218
	v_mov_b32_e32 v31, v219
	v_add_f32_e32 v19, v14, v24
	v_add_f32_e32 v24, v10, v28
	v_add_f32_e32 v25, v15, v25
	v_add_f32_e32 v28, v11, v29
	v_add_f32_e32 v26, v16, v26
	v_add_f32_e32 v29, v12, v30
	v_add_f32_e32 v27, v17, v27
	v_add_f32_e32 v30, v13, v31
	v_mul_f32_e32 v19, 0xbfb8aa3b, v19
	v_mul_f32_e32 v24, 0xbfb8aa3b, v24
	v_mul_f32_e32 v25, 0xbfb8aa3b, v25
	v_mul_f32_e32 v28, 0xbfb8aa3b, v28
	v_mul_f32_e32 v26, 0xbfb8aa3b, v26
	v_mul_f32_e32 v29, 0xbfb8aa3b, v29
	v_mul_f32_e32 v27, 0xbfb8aa3b, v27
	v_mul_f32_e32 v30, 0xbfb8aa3b, v30
	v_exp_f32_e32 v19, v19
	v_exp_f32_e32 v24, v24
	v_exp_f32_e32 v25, v25
	v_exp_f32_e32 v28, v28
	v_exp_f32_e32 v26, v26
	v_exp_f32_e32 v29, v29
	v_exp_f32_e32 v27, v27
	v_exp_f32_e32 v30, v30
	v_add_f32_e32 v19, 1.0, v19
	v_add_f32_e32 v31, 1.0, v24
	v_add_f32_e32 v25, 1.0, v25
	v_add_f32_e32 v33, 1.0, v28
	v_add_f32_e32 v26, 1.0, v26
	v_add_f32_e32 v34, 1.0, v29
	v_add_f32_e32 v27, 1.0, v27
	v_add_f32_e32 v35, 1.0, v30
	v_rcp_f32_e32 v24, v19
	v_rcp_f32_e32 v28, v31
	v_rcp_f32_e32 v25, v25
	v_rcp_f32_e32 v29, v33
	v_rcp_f32_e32 v26, v26
	v_rcp_f32_e32 v30, v34
	v_rcp_f32_e32 v27, v27
	v_rcp_f32_e32 v31, v35

; __device__ __forceinline__ float gelu_tanh(float x) { const float u = x * (-2.302208198f - 0.1029432397f * x * x); return x * __builtin_amdgcn_rcpf(1.f + __builtin_amdgcn_exp2f(u)); }
; __device__ __forceinline__ float sigmoidf_(float x) { return __builtin_amdgcn_rcpf(1.f + __builtin_amdgcn_exp2f(-1.4426950408889634f * x)); }
;     __device__ __forceinline__ void operator()(const f32x4 (&acc)[2][2][4][2], const pg8::Unit& u, int wr, int wc, int fr, int fq, LAS unsigned char* lds, int par) const {
;     ...
;                     if (kind == 0) {
; #pragma unroll
;                         for (int j = 0; j < 4; ++j) { v0[j] = gelu_tanh(v0[j]); v1[j] = gelu_tanh(v1[j]); }
;                     } else if (kind == 1 || kind == 2) {
;                         const int pos = row & (SEQ - 1), i0 = (c & 63) >> 1;
;                         const f32x4 r0 = *(const f32x4*)(rope + ((size_t)pos * 32 + i0) * 2), r1 = *(const f32x4*)(rope + ((size_t)pos * 32 + i0 + 2) * 2);
;                         const float sc = (kind == 1) ? 0.125f : 1.0f;
;                         f32x4 o0, o1;
;                         o0[0] = (v0[0] * r0[0] - v0[1] * r0[1]) * sc; o0[1] = (v0[1] * r0[0] + v0[0] * r0[1]) * sc;
;                         o0[2] = (v0[2] * r0[2] - v0[3] * r0[3]) * sc; o0[3] = (v0[3] * r0[2] + v0[2] * r0[3]) * sc;
;                         o1[0] = (v1[0] * r1[0] - v1[1] * r1[1]) * sc; o1[1] = (v1[1] * r1[0] + v1[0] * r1[1]) * sc;
;                         o1[2] = (v1[2] * r1[2] - v1[3] * r1[3]) * sc; o1[3] = (v1[3] * r1[2] + v1[2] * r1[3]) * sc;
;                         v0 = o0; v1 = o1;
;                     } else if (kind == 4) {
;                         const f32x4 b0 = *(const f32x4*)(bgate + gcol + c), b1 = *(const f32x4*)(bgate + gcol + c + 4);
; #pragma unroll
;                         for (int j = 0; j < 4; ++j) { v0[j] = sigmoidf_(v0[j] + b0[j]); v1[j] = sigmoidf_(v1[j] + b1[j]); }
;                     }
.LBB0_811:
	s_and_b64 vcc, exec, s[50:51]
	s_mov_b64 s[28:29], -1
	s_cbranch_vccnz .LBB0_819
	s_and_b64 vcc, exec, s[48:49]
	s_cbranch_vccnz .LBB0_816
	s_andn2_b64 vcc, exec, s[26:27]
	v_mov_b32_e32 v13, v9
	v_mov_b32_e32 v12, v8
	v_mov_b32_e32 v11, v7
	v_mov_b32_e32 v10, v6
	v_mov_b32_e32 v23, v5
	v_mov_b32_e32 v22, v4
	v_mov_b32_e32 v21, v3
	v_mov_b32_e32 v20, v2
	s_cbranch_vccnz .LBB0_815
	v_mov_b32_e32 v10, v220
	v_mov_b32_e32 v11, v221
	v_mov_b32_e32 v12, v222
	v_mov_b32_e32 v13, v223
	v_mov_b32_e32 v20, v224
	v_mov_b32_e32 v21, v225
	v_mov_b32_e32 v22, v226
	v_mov_b32_e32 v23, v227
	v_add_f32_e32 v0, v6, v10
	v_add_f32_e32 v10, v2, v20
	v_add_f32_e32 v11, v7, v11
	v_add_f32_e32 v20, v3, v21
	v_add_f32_e32 v12, v8, v12
	v_add_f32_e32 v21, v4, v22
	v_add_f32_e32 v13, v9, v13
	v_add_f32_e32 v22, v5, v23
	v_mul_f32_e32 v0, 0xbfb8aa3b, v0
	v_mul_f32_e32 v10, 0xbfb8aa3b, v10
	v_mul_f32_e32 v11, 0xbfb8aa3b, v11
	v_mul_f32_e32 v20, 0xbfb8aa3b, v20
	v_mul_f32_e32 v12, 0xbfb8aa3b, v12
	v_mul_f32_e32 v21, 0xbfb8aa3b, v21
	v_mul_f32_e32 v13, 0xbfb8aa3b, v13
	v_mul_f32_e32 v22, 0xbfb8aa3b, v22
	v_exp_f32_e32 v0, v0
	v_exp_f32_e32 v10, v10
	v_exp_f32_e32 v11, v11
	v_exp_f32_e32 v20, v20
	v_exp_f32_e32 v12, v12
	v_exp_f32_e32 v21, v21
	v_exp_f32_e32 v13, v13
	v_exp_f32_e32 v22, v22
	v_add_f32_e32 v0, 1.0, v0
	v_add_f32_e32 v23, 1.0, v10
	v_add_f32_e32 v11, 1.0, v11
	v_add_f32_e32 v24, 1.0, v20
	v_add_f32_e32 v12, 1.0, v12
	v_add_f32_e32 v25, 1.0, v21
	v_add_f32_e32 v13, 1.0, v13
	v_add_f32_e32 v26, 1.0, v22
	v_rcp_f32_e32 v10, v0
	v_rcp_f32_e32 v20, v23
	v_rcp_f32_e32 v11, v11
	v_rcp_f32_e32 v21, v24
	v_rcp_f32_e32 v12, v12
	v_rcp_f32_e32 v22, v25
	v_rcp_f32_e32 v13, v13
	v_rcp_f32_e32 v23, v26
